# P1 GATES epilogue: sigmoid with packed f32 multiply and add (v_pk_mul_f32 / v_pk_add_f32), in place in the accumulators, 32-bit store offsets
# speedup vs baseline: 1.0023x; 1.0023x over previous
.LBB0_168:
	s_lshl_b32 s1, s0, 8
	s_add_i32 s1, s1, s27
	v_or_b32_e32 v148, s1, v139
	s_cmp_gt_i32 s30, 3
	s_mov_b64 s[14:15], -1
	s_cbranch_scc0 .LBB0_214
	s_cmp_gt_u32 s30, 6
	s_cbranch_scc0 .LBB0_194
	s_cmp_lg_u32 s30, 7
	s_cbranch_scc0 .LBB0_174
	s_cmp_gt_i32 s0, 31
	s_cbranch_scc1 .LBB0_173
	s_lshl_b32 s4, s30, 8
	s_addk_i32 s4, 0xf800
	s_lshl_b64 s[14:15], s[4:5], 1
	v_lshlrev_b32_e32 v136, 1, v138
	v_lshl_add_u32 v149, v148, 13, v136
	v_add_u32_e32 v149, s14, v149
	v_mov_b32_e32 v150, 0xbfb8aa3b
	v_mov_b32_e32 v151, 0xbfb8aa3b
	v_pk_mul_f32 v[124:125], v[124:125], v[150:151]
	v_pk_mul_f32 v[126:127], v[126:127], v[150:151]
	v_pk_mul_f32 v[120:121], v[120:121], v[150:151]
	v_pk_mul_f32 v[122:123], v[122:123], v[150:151]
	v_pk_mul_f32 v[108:109], v[108:109], v[150:151]
	v_pk_mul_f32 v[110:111], v[110:111], v[150:151]
	v_pk_mul_f32 v[104:105], v[104:105], v[150:151]
	v_pk_mul_f32 v[106:107], v[106:107], v[150:151]
	v_exp_f32_e32 v124, v124
	v_exp_f32_e32 v125, v125
	v_exp_f32_e32 v126, v126
	v_exp_f32_e32 v127, v127
	v_exp_f32_e32 v120, v120
	v_exp_f32_e32 v121, v121
	v_exp_f32_e32 v122, v122
	v_exp_f32_e32 v123, v123
	v_exp_f32_e32 v108, v108
	v_exp_f32_e32 v109, v109
	v_exp_f32_e32 v110, v110
	v_exp_f32_e32 v111, v111
	v_exp_f32_e32 v104, v104
	v_exp_f32_e32 v105, v105
	v_exp_f32_e32 v106, v106
	v_exp_f32_e32 v107, v107
	v_pk_add_f32 v[124:125], v[124:125], 1.0 op_sel_hi:[1,0]
	v_pk_add_f32 v[126:127], v[126:127], 1.0 op_sel_hi:[1,0]
	v_pk_add_f32 v[120:121], v[120:121], 1.0 op_sel_hi:[1,0]
	v_pk_add_f32 v[122:123], v[122:123], 1.0 op_sel_hi:[1,0]
	v_pk_add_f32 v[108:109], v[108:109], 1.0 op_sel_hi:[1,0]
	v_pk_add_f32 v[110:111], v[110:111], 1.0 op_sel_hi:[1,0]
	v_pk_add_f32 v[104:105], v[104:105], 1.0 op_sel_hi:[1,0]
	v_pk_add_f32 v[106:107], v[106:107], 1.0 op_sel_hi:[1,0]
	v_rcp_f32_e32 v124, v124
	v_rcp_f32_e32 v125, v125
	v_rcp_f32_e32 v126, v126
	v_rcp_f32_e32 v127, v127
	v_rcp_f32_e32 v120, v120
	v_rcp_f32_e32 v121, v121
	v_rcp_f32_e32 v122, v122
	v_rcp_f32_e32 v123, v123
	v_rcp_f32_e32 v108, v108
	v_rcp_f32_e32 v109, v109
	v_rcp_f32_e32 v110, v110
	v_rcp_f32_e32 v111, v111
	v_rcp_f32_e32 v104, v104
	v_rcp_f32_e32 v105, v105
	v_rcp_f32_e32 v106, v106
	v_rcp_f32_e32 v107, v107
	v_cvt_pk_bf16_f32 v124, v124, v125
	v_cvt_pk_bf16_f32 v125, v126, v127
	v_cvt_pk_bf16_f32 v126, v120, v121
	v_cvt_pk_bf16_f32 v127, v122, v123
	v_cvt_pk_bf16_f32 v108, v108, v109
	v_cvt_pk_bf16_f32 v109, v110, v111
	v_cvt_pk_bf16_f32 v110, v104, v105
	v_cvt_pk_bf16_f32 v111, v106, v107
	v_mov_b32_e32 v152, v149
	global_store_dwordx4 v152, v[124:127], s[8:9]
	global_store_dwordx4 v152, v[108:111], s[8:9] offset:256
	v_pk_mul_f32 v[116:117], v[116:117], v[150:151]
	v_pk_mul_f32 v[118:119], v[118:119], v[150:151]
	v_pk_mul_f32 v[112:113], v[112:113], v[150:151]
	v_pk_mul_f32 v[114:115], v[114:115], v[150:151]
	v_pk_mul_f32 v[92:93], v[92:93], v[150:151]
	v_pk_mul_f32 v[94:95], v[94:95], v[150:151]
	v_pk_mul_f32 v[88:89], v[88:89], v[150:151]
	v_pk_mul_f32 v[90:91], v[90:91], v[150:151]
	v_exp_f32_e32 v116, v116
	v_exp_f32_e32 v117, v117
	v_exp_f32_e32 v118, v118
	v_exp_f32_e32 v119, v119
	v_exp_f32_e32 v112, v112
	v_exp_f32_e32 v113, v113
	v_exp_f32_e32 v114, v114
	v_exp_f32_e32 v115, v115
	v_exp_f32_e32 v92, v92
	v_exp_f32_e32 v93, v93
	v_exp_f32_e32 v94, v94
	v_exp_f32_e32 v95, v95
	v_exp_f32_e32 v88, v88
	v_exp_f32_e32 v89, v89
	v_exp_f32_e32 v90, v90
	v_exp_f32_e32 v91, v91
	v_pk_add_f32 v[116:117], v[116:117], 1.0 op_sel_hi:[1,0]
	v_pk_add_f32 v[118:119], v[118:119], 1.0 op_sel_hi:[1,0]
	v_pk_add_f32 v[112:113], v[112:113], 1.0 op_sel_hi:[1,0]
	v_pk_add_f32 v[114:115], v[114:115], 1.0 op_sel_hi:[1,0]
	v_pk_add_f32 v[92:93], v[92:93], 1.0 op_sel_hi:[1,0]
	v_pk_add_f32 v[94:95], v[94:95], 1.0 op_sel_hi:[1,0]
	v_pk_add_f32 v[88:89], v[88:89], 1.0 op_sel_hi:[1,0]
	v_pk_add_f32 v[90:91], v[90:91], 1.0 op_sel_hi:[1,0]
	v_rcp_f32_e32 v116, v116
	v_rcp_f32_e32 v117, v117
	v_rcp_f32_e32 v118, v118
	v_rcp_f32_e32 v119, v119
	v_rcp_f32_e32 v112, v112
	v_rcp_f32_e32 v113, v113
	v_rcp_f32_e32 v114, v114
	v_rcp_f32_e32 v115, v115
	v_rcp_f32_e32 v92, v92
	v_rcp_f32_e32 v93, v93
	v_rcp_f32_e32 v94, v94
	v_rcp_f32_e32 v95, v95
	v_rcp_f32_e32 v88, v88
	v_rcp_f32_e32 v89, v89
	v_rcp_f32_e32 v90, v90
	v_rcp_f32_e32 v91, v91
	v_cvt_pk_bf16_f32 v116, v116, v117
	v_cvt_pk_bf16_f32 v117, v118, v119
	v_cvt_pk_bf16_f32 v118, v112, v113
	v_cvt_pk_bf16_f32 v119, v114, v115
	v_cvt_pk_bf16_f32 v92, v92, v93
	v_cvt_pk_bf16_f32 v93, v94, v95
	v_cvt_pk_bf16_f32 v94, v88, v89
	v_cvt_pk_bf16_f32 v95, v90, v91
	v_add_u32_e32 v152, 0x20000, v149
	global_store_dwordx4 v152, v[116:119], s[8:9]
	global_store_dwordx4 v152, v[92:95], s[8:9] offset:256
	v_pk_mul_f32 v[100:101], v[100:101], v[150:151]
	v_pk_mul_f32 v[102:103], v[102:103], v[150:151]
	v_pk_mul_f32 v[96:97], v[96:97], v[150:151]
	v_pk_mul_f32 v[98:99], v[98:99], v[150:151]
	v_pk_mul_f32 v[76:77], v[76:77], v[150:151]
	v_pk_mul_f32 v[78:79], v[78:79], v[150:151]
	v_pk_mul_f32 v[72:73], v[72:73], v[150:151]
	v_pk_mul_f32 v[74:75], v[74:75], v[150:151]
	v_exp_f32_e32 v100, v100
	v_exp_f32_e32 v101, v101
	v_exp_f32_e32 v102, v102
	v_exp_f32_e32 v103, v103
	v_exp_f32_e32 v96, v96
	v_exp_f32_e32 v97, v97
	v_exp_f32_e32 v98, v98
	v_exp_f32_e32 v99, v99
	v_exp_f32_e32 v76, v76
	v_exp_f32_e32 v77, v77
	v_exp_f32_e32 v78, v78
	v_exp_f32_e32 v79, v79
	v_exp_f32_e32 v72, v72
	v_exp_f32_e32 v73, v73
	v_exp_f32_e32 v74, v74
	v_exp_f32_e32 v75, v75
	v_pk_add_f32 v[100:101], v[100:101], 1.0 op_sel_hi:[1,0]
	v_pk_add_f32 v[102:103], v[102:103], 1.0 op_sel_hi:[1,0]
	v_pk_add_f32 v[96:97], v[96:97], 1.0 op_sel_hi:[1,0]
	v_pk_add_f32 v[98:99], v[98:99], 1.0 op_sel_hi:[1,0]
	v_pk_add_f32 v[76:77], v[76:77], 1.0 op_sel_hi:[1,0]
	v_pk_add_f32 v[78:79], v[78:79], 1.0 op_sel_hi:[1,0]
	v_pk_add_f32 v[72:73], v[72:73], 1.0 op_sel_hi:[1,0]
	v_pk_add_f32 v[74:75], v[74:75], 1.0 op_sel_hi:[1,0]
	v_rcp_f32_e32 v100, v100
	v_rcp_f32_e32 v101, v101
	v_rcp_f32_e32 v102, v102
	v_rcp_f32_e32 v103, v103
	v_rcp_f32_e32 v96, v96
	v_rcp_f32_e32 v97, v97
	v_rcp_f32_e32 v98, v98
	v_rcp_f32_e32 v99, v99
	v_rcp_f32_e32 v76, v76
	v_rcp_f32_e32 v77, v77
	v_rcp_f32_e32 v78, v78
	v_rcp_f32_e32 v79, v79
	v_rcp_f32_e32 v72, v72
	v_rcp_f32_e32 v73, v73
	v_rcp_f32_e32 v74, v74
	v_rcp_f32_e32 v75, v75
	v_cvt_pk_bf16_f32 v100, v100, v101
	v_cvt_pk_bf16_f32 v101, v102, v103
	v_cvt_pk_bf16_f32 v102, v96, v97
	v_cvt_pk_bf16_f32 v103, v98, v99
	v_cvt_pk_bf16_f32 v76, v76, v77
	v_cvt_pk_bf16_f32 v77, v78, v79
	v_cvt_pk_bf16_f32 v78, v72, v73
	v_cvt_pk_bf16_f32 v79, v74, v75
	v_add_u32_e32 v152, 0x40000, v149
	global_store_dwordx4 v152, v[100:103], s[8:9]
	global_store_dwordx4 v152, v[76:79], s[8:9] offset:256
	v_pk_mul_f32 v[84:85], v[84:85], v[150:151]
	v_pk_mul_f32 v[86:87], v[86:87], v[150:151]
	v_pk_mul_f32 v[80:81], v[80:81], v[150:151]
	v_pk_mul_f32 v[82:83], v[82:83], v[150:151]
	v_pk_mul_f32 v[68:69], v[68:69], v[150:151]
	v_pk_mul_f32 v[70:71], v[70:71], v[150:151]
	v_pk_mul_f32 v[64:65], v[64:65], v[150:151]
	v_pk_mul_f32 v[66:67], v[66:67], v[150:151]
	v_exp_f32_e32 v84, v84
	v_exp_f32_e32 v85, v85
	v_exp_f32_e32 v86, v86
	v_exp_f32_e32 v87, v87
	v_exp_f32_e32 v80, v80
	v_exp_f32_e32 v81, v81
	v_exp_f32_e32 v82, v82
	v_exp_f32_e32 v83, v83
	v_exp_f32_e32 v68, v68
	v_exp_f32_e32 v69, v69
	v_exp_f32_e32 v70, v70
	v_exp_f32_e32 v71, v71
	v_exp_f32_e32 v64, v64
	v_exp_f32_e32 v65, v65
	v_exp_f32_e32 v66, v66
	v_exp_f32_e32 v67, v67
	v_pk_add_f32 v[84:85], v[84:85], 1.0 op_sel_hi:[1,0]
	v_pk_add_f32 v[86:87], v[86:87], 1.0 op_sel_hi:[1,0]
	v_pk_add_f32 v[80:81], v[80:81], 1.0 op_sel_hi:[1,0]
	v_pk_add_f32 v[82:83], v[82:83], 1.0 op_sel_hi:[1,0]
	v_pk_add_f32 v[68:69], v[68:69], 1.0 op_sel_hi:[1,0]
	v_pk_add_f32 v[70:71], v[70:71], 1.0 op_sel_hi:[1,0]
	v_pk_add_f32 v[64:65], v[64:65], 1.0 op_sel_hi:[1,0]
	v_pk_add_f32 v[66:67], v[66:67], 1.0 op_sel_hi:[1,0]
	v_rcp_f32_e32 v84, v84
	v_rcp_f32_e32 v85, v85
	v_rcp_f32_e32 v86, v86
	v_rcp_f32_e32 v87, v87
	v_rcp_f32_e32 v80, v80
	v_rcp_f32_e32 v81, v81
	v_rcp_f32_e32 v82, v82
	v_rcp_f32_e32 v83, v83
	v_rcp_f32_e32 v68, v68
	v_rcp_f32_e32 v69, v69
	v_rcp_f32_e32 v70, v70
	v_rcp_f32_e32 v71, v71
	v_rcp_f32_e32 v64, v64
	v_rcp_f32_e32 v65, v65
	v_rcp_f32_e32 v66, v66
	v_rcp_f32_e32 v67, v67
	v_cvt_pk_bf16_f32 v84, v84, v85
	v_cvt_pk_bf16_f32 v85, v86, v87
	v_cvt_pk_bf16_f32 v86, v80, v81
	v_cvt_pk_bf16_f32 v87, v82, v83
	v_cvt_pk_bf16_f32 v68, v68, v69
	v_cvt_pk_bf16_f32 v69, v70, v71
	v_cvt_pk_bf16_f32 v70, v64, v65
	v_cvt_pk_bf16_f32 v71, v66, v67
	v_add_u32_e32 v152, 0x60000, v149
	global_store_dwordx4 v152, v[84:87], s[8:9]
	global_store_dwordx4 v152, v[68:71], s[8:9] offset:256
	v_pk_mul_f32 v[60:61], v[60:61], v[150:151]
	v_pk_mul_f32 v[62:63], v[62:63], v[150:151]
	v_pk_mul_f32 v[56:57], v[56:57], v[150:151]
	v_pk_mul_f32 v[58:59], v[58:59], v[150:151]
	v_pk_mul_f32 v[44:45], v[44:45], v[150:151]
	v_pk_mul_f32 v[46:47], v[46:47], v[150:151]
	v_pk_mul_f32 v[40:41], v[40:41], v[150:151]
	v_pk_mul_f32 v[42:43], v[42:43], v[150:151]
	v_exp_f32_e32 v60, v60
	v_exp_f32_e32 v61, v61
	v_exp_f32_e32 v62, v62
	v_exp_f32_e32 v63, v63
	v_exp_f32_e32 v56, v56
	v_exp_f32_e32 v57, v57
	v_exp_f32_e32 v58, v58
	v_exp_f32_e32 v59, v59
	v_exp_f32_e32 v44, v44
	v_exp_f32_e32 v45, v45
	v_exp_f32_e32 v46, v46
	v_exp_f32_e32 v47, v47
	v_exp_f32_e32 v40, v40
	v_exp_f32_e32 v41, v41
	v_exp_f32_e32 v42, v42
	v_exp_f32_e32 v43, v43
	v_pk_add_f32 v[60:61], v[60:61], 1.0 op_sel_hi:[1,0]
	v_pk_add_f32 v[62:63], v[62:63], 1.0 op_sel_hi:[1,0]
	v_pk_add_f32 v[56:57], v[56:57], 1.0 op_sel_hi:[1,0]
	v_pk_add_f32 v[58:59], v[58:59], 1.0 op_sel_hi:[1,0]
	v_pk_add_f32 v[44:45], v[44:45], 1.0 op_sel_hi:[1,0]
	v_pk_add_f32 v[46:47], v[46:47], 1.0 op_sel_hi:[1,0]
	v_pk_add_f32 v[40:41], v[40:41], 1.0 op_sel_hi:[1,0]
	v_pk_add_f32 v[42:43], v[42:43], 1.0 op_sel_hi:[1,0]
	v_rcp_f32_e32 v60, v60
	v_rcp_f32_e32 v61, v61
	v_rcp_f32_e32 v62, v62
	v_rcp_f32_e32 v63, v63
	v_rcp_f32_e32 v56, v56
	v_rcp_f32_e32 v57, v57
	v_rcp_f32_e32 v58, v58
	v_rcp_f32_e32 v59, v59
	v_rcp_f32_e32 v44, v44
	v_rcp_f32_e32 v45, v45
	v_rcp_f32_e32 v46, v46
	v_rcp_f32_e32 v47, v47
	v_rcp_f32_e32 v40, v40
	v_rcp_f32_e32 v41, v41
	v_rcp_f32_e32 v42, v42
	v_rcp_f32_e32 v43, v43
	v_cvt_pk_bf16_f32 v60, v60, v61
	v_cvt_pk_bf16_f32 v61, v62, v63
	v_cvt_pk_bf16_f32 v62, v56, v57
	v_cvt_pk_bf16_f32 v63, v58, v59
	v_cvt_pk_bf16_f32 v44, v44, v45
	v_cvt_pk_bf16_f32 v45, v46, v47
	v_cvt_pk_bf16_f32 v46, v40, v41
	v_cvt_pk_bf16_f32 v47, v42, v43
	v_add_u32_e32 v152, 0x100000, v149
	global_store_dwordx4 v152, v[60:63], s[8:9]
	global_store_dwordx4 v152, v[44:47], s[8:9] offset:256
	v_pk_mul_f32 v[52:53], v[52:53], v[150:151]
	v_pk_mul_f32 v[54:55], v[54:55], v[150:151]
	v_pk_mul_f32 v[48:49], v[48:49], v[150:151]
	v_pk_mul_f32 v[50:51], v[50:51], v[150:151]
	v_pk_mul_f32 v[28:29], v[28:29], v[150:151]
	v_pk_mul_f32 v[30:31], v[30:31], v[150:151]
	v_pk_mul_f32 v[24:25], v[24:25], v[150:151]
	v_pk_mul_f32 v[26:27], v[26:27], v[150:151]
	v_exp_f32_e32 v52, v52
	v_exp_f32_e32 v53, v53
	v_exp_f32_e32 v54, v54
	v_exp_f32_e32 v55, v55
	v_exp_f32_e32 v48, v48
	v_exp_f32_e32 v49, v49
	v_exp_f32_e32 v50, v50
	v_exp_f32_e32 v51, v51
	v_exp_f32_e32 v28, v28
	v_exp_f32_e32 v29, v29
	v_exp_f32_e32 v30, v30
	v_exp_f32_e32 v31, v31
	v_exp_f32_e32 v24, v24
	v_exp_f32_e32 v25, v25
	v_exp_f32_e32 v26, v26
	v_exp_f32_e32 v27, v27
	v_pk_add_f32 v[52:53], v[52:53], 1.0 op_sel_hi:[1,0]
	v_pk_add_f32 v[54:55], v[54:55], 1.0 op_sel_hi:[1,0]
	v_pk_add_f32 v[48:49], v[48:49], 1.0 op_sel_hi:[1,0]
	v_pk_add_f32 v[50:51], v[50:51], 1.0 op_sel_hi:[1,0]
	v_pk_add_f32 v[28:29], v[28:29], 1.0 op_sel_hi:[1,0]
	v_pk_add_f32 v[30:31], v[30:31], 1.0 op_sel_hi:[1,0]
	v_pk_add_f32 v[24:25], v[24:25], 1.0 op_sel_hi:[1,0]
	v_pk_add_f32 v[26:27], v[26:27], 1.0 op_sel_hi:[1,0]
	v_rcp_f32_e32 v52, v52
	v_rcp_f32_e32 v53, v53
	v_rcp_f32_e32 v54, v54
	v_rcp_f32_e32 v55, v55
	v_rcp_f32_e32 v48, v48
	v_rcp_f32_e32 v49, v49
	v_rcp_f32_e32 v50, v50
	v_rcp_f32_e32 v51, v51
	v_rcp_f32_e32 v28, v28
	v_rcp_f32_e32 v29, v29
	v_rcp_f32_e32 v30, v30
	v_rcp_f32_e32 v31, v31
	v_rcp_f32_e32 v24, v24
	v_rcp_f32_e32 v25, v25
	v_rcp_f32_e32 v26, v26
	v_rcp_f32_e32 v27, v27
	v_cvt_pk_bf16_f32 v52, v52, v53
	v_cvt_pk_bf16_f32 v53, v54, v55
	v_cvt_pk_bf16_f32 v54, v48, v49
	v_cvt_pk_bf16_f32 v55, v50, v51
	v_cvt_pk_bf16_f32 v28, v28, v29
	v_cvt_pk_bf16_f32 v29, v30, v31
	v_cvt_pk_bf16_f32 v30, v24, v25
	v_cvt_pk_bf16_f32 v31, v26, v27
	v_add_u32_e32 v152, 0x120000, v149
	global_store_dwordx4 v152, v[52:55], s[8:9]
	global_store_dwordx4 v152, v[28:31], s[8:9] offset:256
	v_pk_mul_f32 v[36:37], v[36:37], v[150:151]
	v_pk_mul_f32 v[38:39], v[38:39], v[150:151]
	v_pk_mul_f32 v[32:33], v[32:33], v[150:151]
	v_pk_mul_f32 v[34:35], v[34:35], v[150:151]
	v_pk_mul_f32 v[12:13], v[12:13], v[150:151]
	v_pk_mul_f32 v[14:15], v[14:15], v[150:151]
	v_pk_mul_f32 v[8:9], v[8:9], v[150:151]
	v_pk_mul_f32 v[10:11], v[10:11], v[150:151]
	v_exp_f32_e32 v36, v36
	v_exp_f32_e32 v37, v37
	v_exp_f32_e32 v38, v38
	v_exp_f32_e32 v39, v39
	v_exp_f32_e32 v32, v32
	v_exp_f32_e32 v33, v33
	v_exp_f32_e32 v34, v34
	v_exp_f32_e32 v35, v35
	v_exp_f32_e32 v12, v12
	v_exp_f32_e32 v13, v13
	v_exp_f32_e32 v14, v14
	v_exp_f32_e32 v15, v15
	v_exp_f32_e32 v8, v8
	v_exp_f32_e32 v9, v9
	v_exp_f32_e32 v10, v10
	v_exp_f32_e32 v11, v11
	v_pk_add_f32 v[36:37], v[36:37], 1.0 op_sel_hi:[1,0]
	v_pk_add_f32 v[38:39], v[38:39], 1.0 op_sel_hi:[1,0]
	v_pk_add_f32 v[32:33], v[32:33], 1.0 op_sel_hi:[1,0]
	v_pk_add_f32 v[34:35], v[34:35], 1.0 op_sel_hi:[1,0]
	v_pk_add_f32 v[12:13], v[12:13], 1.0 op_sel_hi:[1,0]
	v_pk_add_f32 v[14:15], v[14:15], 1.0 op_sel_hi:[1,0]
	v_pk_add_f32 v[8:9], v[8:9], 1.0 op_sel_hi:[1,0]
	v_pk_add_f32 v[10:11], v[10:11], 1.0 op_sel_hi:[1,0]
	v_rcp_f32_e32 v36, v36
	v_rcp_f32_e32 v37, v37
	v_rcp_f32_e32 v38, v38
	v_rcp_f32_e32 v39, v39
	v_rcp_f32_e32 v32, v32
	v_rcp_f32_e32 v33, v33
	v_rcp_f32_e32 v34, v34
	v_rcp_f32_e32 v35, v35
	v_rcp_f32_e32 v12, v12
	v_rcp_f32_e32 v13, v13
	v_rcp_f32_e32 v14, v14
	v_rcp_f32_e32 v15, v15
	v_rcp_f32_e32 v8, v8
	v_rcp_f32_e32 v9, v9
	v_rcp_f32_e32 v10, v10
	v_rcp_f32_e32 v11, v11
	v_cvt_pk_bf16_f32 v36, v36, v37
	v_cvt_pk_bf16_f32 v37, v38, v39
	v_cvt_pk_bf16_f32 v38, v32, v33
	v_cvt_pk_bf16_f32 v39, v34, v35
	v_cvt_pk_bf16_f32 v12, v12, v13
	v_cvt_pk_bf16_f32 v13, v14, v15
	v_cvt_pk_bf16_f32 v14, v8, v9
	v_cvt_pk_bf16_f32 v15, v10, v11
	v_add_u32_e32 v152, 0x140000, v149
	global_store_dwordx4 v152, v[36:39], s[8:9]
	global_store_dwordx4 v152, v[12:15], s[8:9] offset:256
	v_pk_mul_f32 v[20:21], v[20:21], v[150:151]
	v_pk_mul_f32 v[22:23], v[22:23], v[150:151]
	v_pk_mul_f32 v[16:17], v[16:17], v[150:151]
	v_pk_mul_f32 v[18:19], v[18:19], v[150:151]
	v_pk_mul_f32 v[4:5], v[4:5], v[150:151]
	v_pk_mul_f32 v[6:7], v[6:7], v[150:151]
	v_pk_mul_f32 v[0:1], v[0:1], v[150:151]
	v_pk_mul_f32 v[2:3], v[2:3], v[150:151]
	v_exp_f32_e32 v20, v20
	v_exp_f32_e32 v21, v21
	v_exp_f32_e32 v22, v22
	v_exp_f32_e32 v23, v23
	v_exp_f32_e32 v16, v16
	v_exp_f32_e32 v17, v17
	v_exp_f32_e32 v18, v18
	v_exp_f32_e32 v19, v19
	v_exp_f32_e32 v4, v4
	v_exp_f32_e32 v5, v5
	v_exp_f32_e32 v6, v6
	v_exp_f32_e32 v7, v7
	v_exp_f32_e32 v0, v0
	v_exp_f32_e32 v1, v1
	v_exp_f32_e32 v2, v2
	v_exp_f32_e32 v3, v3
	v_pk_add_f32 v[20:21], v[20:21], 1.0 op_sel_hi:[1,0]
	v_pk_add_f32 v[22:23], v[22:23], 1.0 op_sel_hi:[1,0]
	v_pk_add_f32 v[16:17], v[16:17], 1.0 op_sel_hi:[1,0]
	v_pk_add_f32 v[18:19], v[18:19], 1.0 op_sel_hi:[1,0]
	v_pk_add_f32 v[4:5], v[4:5], 1.0 op_sel_hi:[1,0]
	v_pk_add_f32 v[6:7], v[6:7], 1.0 op_sel_hi:[1,0]
	v_pk_add_f32 v[0:1], v[0:1], 1.0 op_sel_hi:[1,0]
	v_pk_add_f32 v[2:3], v[2:3], 1.0 op_sel_hi:[1,0]
	v_rcp_f32_e32 v20, v20
	v_rcp_f32_e32 v21, v21
	v_rcp_f32_e32 v22, v22
	v_rcp_f32_e32 v23, v23
	v_rcp_f32_e32 v16, v16
	v_rcp_f32_e32 v17, v17
	v_rcp_f32_e32 v18, v18
	v_rcp_f32_e32 v19, v19
	v_rcp_f32_e32 v4, v4
	v_rcp_f32_e32 v5, v5
	v_rcp_f32_e32 v6, v6
	v_rcp_f32_e32 v7, v7
	v_rcp_f32_e32 v0, v0
	v_rcp_f32_e32 v1, v1
	v_rcp_f32_e32 v2, v2
	v_rcp_f32_e32 v3, v3
	v_cvt_pk_bf16_f32 v20, v20, v21
	v_cvt_pk_bf16_f32 v21, v22, v23
	v_cvt_pk_bf16_f32 v22, v16, v17
	v_cvt_pk_bf16_f32 v23, v18, v19
	v_cvt_pk_bf16_f32 v4, v4, v5
	v_cvt_pk_bf16_f32 v5, v6, v7
	v_cvt_pk_bf16_f32 v6, v0, v1
	v_cvt_pk_bf16_f32 v7, v2, v3
	v_add_u32_e32 v152, 0x160000, v149
	global_store_dwordx4 v152, v[20:23], s[8:9]
	global_store_dwordx4 v152, v[4:7], s[8:9] offset:256
	s_mov_b32 s4, 0x160000
